# scan loader LDS-DMA with nt policy (once-read chunk operands)
# baseline (speedup 1.0000x reference)
.LBB0_121:
	s_andn2_b64 vcc, exec, s[0:1]
	s_cbranch_vccnz .LBB0_123
	s_cmp_eq_u32 s2, 0
	s_cselect_b32 s1, 0, 0xbce800
	s_mov_b32 s0, 0x61800
	s_cselect_b32 s0, s0, 0xb6d000
	s_add_u32 s6, s23, s1
	s_addc_u32 s7, s28, 0
	s_add_u32 s1, s6, s29
	s_addc_u32 s5, s7, 0
	s_add_u32 s8, s1, 0x4000
	s_addc_u32 s9, s5, 0
	s_add_u32 s1, s6, 0x10000
	s_addc_u32 s5, s7, 0
	v_readlane_b32 s37, v249, 53
	s_add_u32 s12, s6, s37
	v_readlane_b32 s46, v249, 54
	s_addc_u32 s13, s7, s46
	v_readlane_b32 s43, v249, 52
	s_add_u32 s14, s8, s43
	v_readlane_b32 s44, v249, 50
	s_addc_u32 s15, s9, 0
	v_readlane_b32 s45, v249, 51
	s_and_b64 s[10:11], s[44:45], exec
	s_cselect_b32 s11, s12, s14
	v_readlane_b32 s42, v249, 25
	s_cselect_b32 s10, s13, s15
	s_add_u32 s12, s11, s42
	s_addc_u32 s13, s10, 0
	s_and_b64 s[10:11], s[70:71], exec
	v_readlane_b32 s34, v249, 58
	s_cselect_b32 s11, s5, s13
	s_cselect_b32 s10, s1, s12
	s_add_u32 s12, s6, s34
	v_readlane_b32 s48, v249, 59
	s_addc_u32 s13, s7, s48
	v_readlane_b32 s47, v249, 57
	s_add_u32 s14, s8, s47
	v_readlane_b32 vcc_lo, v249, 55
	v_lshl_add_u64 v[0:1], s[10:11], 0, v[40:41]
	v_readlane_b32 s11, v250, 50
	s_addc_u32 s15, s9, 0
	v_readlane_b32 vcc_hi, v249, 56
	s_mov_b32 s10, m0
	s_mov_b32 m0, s11
	s_nop 0
	global_load_lds_dwordx4 v[0:1], off nt
	s_mov_b32 m0, s10
	s_and_b64 s[10:11], vcc, exec
	s_cselect_b32 s11, s12, s14
	v_readlane_b32 s36, v249, 23
	s_cselect_b32 s10, s13, s15
	s_add_u32 s12, s11, s36
	s_addc_u32 s13, s10, 0
	s_and_b64 s[10:11], s[70:71], exec
	s_cselect_b32 s11, s5, s13
	s_cselect_b32 s10, s1, s12
	v_lshl_add_u64 v[0:1], s[10:11], 0, v[40:41]
	v_readlane_b32 s11, v250, 52
	s_mov_b32 s10, m0
	s_mov_b32 m0, s11
	s_nop 0
	global_load_lds_dwordx4 v[0:1], off nt
	s_mov_b32 m0, s10
	v_readlane_b32 s18, v249, 63
	s_add_u32 s12, s6, s18
	v_readlane_b32 s10, v250, 0
	s_addc_u32 s13, s7, s10
	v_readlane_b32 s10, v249, 62
	s_add_u32 s14, s8, s10
	v_readlane_b32 s62, v249, 60
	s_addc_u32 s15, s9, 0
	v_readlane_b32 s63, v249, 61
	s_and_b64 s[10:11], s[62:63], exec
	s_cselect_b32 s11, s12, s14
	v_readlane_b32 s19, v249, 21
	s_cselect_b32 s10, s13, s15
	s_add_u32 s12, s11, s19
	s_addc_u32 s13, s10, 0
	s_and_b64 s[10:11], s[70:71], exec
	v_readlane_b32 s16, v250, 4
	s_cselect_b32 s11, s5, s13
	s_cselect_b32 s10, s1, s12
	s_add_u32 s12, s6, s16
	s_addc_u32 s13, s7, s97
	s_add_u32 s14, s8, s96
	s_mov_b32 s67, s96
	s_mov_b32 s83, s26
	s_mov_b32 s26, s97
	v_readlane_b32 s96, v250, 1
	v_lshl_add_u64 v[0:1], s[10:11], 0, v[40:41]
	v_readlane_b32 s11, v250, 54
	s_addc_u32 s15, s9, 0
	v_readlane_b32 s97, v250, 2
	s_mov_b32 s10, m0
	s_mov_b32 m0, s11
	s_nop 0
	global_load_lds_dwordx4 v[0:1], off nt
	s_mov_b32 m0, s10
	s_and_b64 s[10:11], s[96:97], exec
	s_cselect_b32 s11, s12, s14
	v_readlane_b32 s17, v249, 19
	s_cselect_b32 s10, s13, s15
	s_add_u32 s12, s11, s17
	s_addc_u32 s13, s10, 0
	s_and_b64 s[10:11], s[70:71], exec
	s_cselect_b32 s11, s5, s13
	s_cselect_b32 s10, s1, s12
	s_add_u32 s12, s6, s61
	v_readlane_b32 s49, v250, 11
	s_addc_u32 s13, s7, s49
	v_readlane_b32 s52, v250, 9
	s_add_u32 s14, s8, s52
	s_mov_b32 s33, s84
	v_readlane_b32 s84, v250, 7
	v_lshl_add_u64 v[0:1], s[10:11], 0, v[40:41]
	v_readlane_b32 s11, v250, 56
	s_addc_u32 s15, s9, 0
	v_readlane_b32 s85, v250, 8
	s_mov_b32 s10, m0
	s_mov_b32 m0, s11
	s_nop 0
	global_load_lds_dwordx4 v[0:1], off nt
	s_mov_b32 m0, s10
	s_and_b64 s[10:11], s[84:85], exec
	s_cselect_b32 s11, s12, s14
	v_readlane_b32 s53, v255, 17
	s_cselect_b32 s10, s13, s15
	s_add_u32 s12, s11, s53
	s_addc_u32 s13, s10, 0
	s_and_b64 s[10:11], s[70:71], exec
	s_cselect_b32 s11, s5, s13
	s_cselect_b32 s10, s1, s12
	s_add_u32 s12, s6, s57
	s_addc_u32 s13, s7, s33
	s_add_u32 s14, s8, s91
	v_readlane_b32 s30, v250, 12
	v_lshl_add_u64 v[0:1], s[10:11], 0, v[40:41]
	v_readlane_b32 s11, v250, 58
	s_addc_u32 s15, s9, 0
	v_readlane_b32 s31, v250, 13
	s_mov_b32 s10, m0
	s_mov_b32 m0, s11
	s_nop 0
	global_load_lds_dwordx4 v[0:1], off nt
	s_mov_b32 m0, s10
	s_and_b64 s[10:11], s[30:31], exec
	s_cselect_b32 s11, s12, s14
	s_cselect_b32 s10, s13, s15
	s_add_u32 s12, s11, s58
	s_addc_u32 s13, s10, 0
	s_and_b64 s[10:11], s[70:71], exec
	s_cselect_b32 s11, s5, s13
	s_cselect_b32 s10, s1, s12
	s_add_u32 s12, s6, s59
	s_addc_u32 s13, s7, s83
	s_add_u32 s14, s8, s93
	v_lshl_add_u64 v[0:1], s[10:11], 0, v[40:41]
	v_readlane_b32 s11, v250, 60
	s_addc_u32 s15, s9, 0
	s_mov_b32 s10, m0
	s_mov_b32 m0, s11
	s_nop 0
	global_load_lds_dwordx4 v[0:1], off nt
	s_mov_b32 m0, s10
	s_and_b64 s[10:11], s[20:21], exec
	s_cselect_b32 s11, s12, s14
	s_cselect_b32 s10, s13, s15
	s_add_u32 s12, s11, s60
	s_addc_u32 s13, s10, 0
	s_and_b64 s[10:11], s[70:71], exec
	s_cselect_b32 s11, s5, s13
	s_cselect_b32 s10, s1, s12
	s_add_u32 s12, s6, s94
	v_readlane_b32 s80, v250, 36
	s_addc_u32 s13, s7, s80
	v_readlane_b32 s82, v250, 34
	s_add_u32 s14, s8, s82
	v_readlane_b32 s72, v250, 32
	v_lshl_add_u64 v[0:1], s[10:11], 0, v[40:41]
	v_readlane_b32 s11, v250, 62
	s_addc_u32 s15, s9, 0
	v_readlane_b32 s73, v250, 33
	s_mov_b32 s10, m0
	s_mov_b32 m0, s11
	s_nop 0
	global_load_lds_dwordx4 v[0:1], off nt
	s_mov_b32 m0, s10
	s_and_b64 s[10:11], s[72:73], exec
	s_cselect_b32 s11, s12, s14
	s_cselect_b32 s10, s13, s15
	s_add_u32 s12, s11, s56
	s_addc_u32 s13, s10, 0
	s_and_b64 s[10:11], s[86:87], exec
	s_cselect_b32 s11, s5, s13
	s_cselect_b32 s10, s1, s12
	s_add_u32 s12, s6, s77
	v_readlane_b32 s78, v250, 41
	s_addc_u32 s13, s7, s78
	v_readlane_b32 s79, v250, 39
	s_add_u32 s14, s8, s79
	s_mov_b32 s40, s75
	v_readlane_b32 s74, v250, 37
	v_lshl_add_u64 v[0:1], s[10:11], 0, v[40:41]
	v_readlane_b32 s11, v251, 0
	s_addc_u32 s15, s9, 0
	v_readlane_b32 s75, v250, 38
	s_mov_b32 s10, m0
	s_mov_b32 m0, s11
	s_nop 0
	global_load_lds_dwordx4 v[0:1], off nt
	s_mov_b32 m0, s10
	s_and_b64 s[10:11], s[74:75], exec
	s_cselect_b32 s11, s12, s14
	s_cselect_b32 s10, s13, s15
	s_add_u32 s12, s11, s27
	s_addc_u32 s13, s10, 0
	s_and_b64 s[10:11], s[86:87], exec
	s_cselect_b32 s11, s5, s13
	s_cselect_b32 s10, s1, s12
	s_add_u32 s12, s6, s24
	v_readlane_b32 s90, v250, 46
	s_addc_u32 s13, s7, s90
	s_mov_b32 s41, s81
	v_readlane_b32 s81, v250, 44
	s_add_u32 s14, s8, s81
	s_mov_b64 s[50:51], s[88:89]
	v_readlane_b32 s88, v250, 42
	v_lshl_add_u64 v[0:1], s[10:11], 0, v[40:41]
	v_readlane_b32 s11, v251, 2
	s_addc_u32 s15, s9, 0
	v_readlane_b32 s89, v250, 43
	s_mov_b32 s10, m0
	s_mov_b32 m0, s11
	s_nop 0
	global_load_lds_dwordx4 v[0:1], off nt
	s_mov_b32 m0, s10
	s_and_b64 s[10:11], s[88:89], exec
	s_cselect_b32 s11, s12, s14
	s_cselect_b32 s10, s13, s15
	s_add_u32 s12, s11, s66
	s_addc_u32 s13, s10, 0
	s_and_b64 s[10:11], s[86:87], exec
	s_cselect_b32 s11, s5, s13
	s_cselect_b32 s10, s1, s12
	v_lshl_add_u64 v[0:1], s[10:11], 0, v[40:41]
	v_readlane_b32 s11, v251, 4
	s_mov_b32 s10, m0
	s_mov_b32 m0, s11
	s_nop 0
	global_load_lds_dwordx4 v[0:1], off nt
	s_mov_b32 m0, s10
	s_add_u32 s10, s6, s22
	s_addc_u32 s11, s7, s64
	s_add_u32 s8, s8, s65
	s_addc_u32 s9, s9, 0
	s_and_b64 s[6:7], s[68:69], exec
	s_cselect_b32 s7, s10, s8
	s_cselect_b32 s6, s11, s9
	s_add_u32 s8, s7, s76
	s_addc_u32 s9, s6, 0
	s_and_b64 s[6:7], s[86:87], exec
	s_cselect_b32 s7, s5, s9
	s_cselect_b32 s6, s1, s8
	v_readlane_b32 s5, v251, 6
	v_lshl_add_u64 v[0:1], s[6:7], 0, v[40:41]
	s_mov_b32 s1, m0
	s_mov_b32 m0, s5
	s_nop 0
	global_load_lds_dwordx4 v[0:1], off nt
	s_mov_b32 m0, s1
	s_add_u32 s5, s23, s0
	s_addc_u32 s6, s28, 0
	s_add_u32 s0, s5, s29
	s_addc_u32 s1, s6, 0
	s_add_u32 s7, s0, 0x4000
	s_addc_u32 s8, s1, 0
	s_add_u32 s0, s5, 0x10000
	s_addc_u32 s1, s6, 0
	s_add_u32 s9, s5, s37
	s_addc_u32 s12, s6, s46
	s_add_u32 s13, s7, s43
	s_addc_u32 s14, s8, 0
	s_and_b64 s[10:11], s[44:45], exec
	s_cselect_b32 s9, s9, s13
	s_cselect_b32 s10, s12, s14
	s_add_u32 s9, s9, s42
	s_addc_u32 s12, s10, 0
	s_and_b64 s[10:11], s[70:71], exec
	s_cselect_b32 s11, s1, s12
	s_cselect_b32 s10, s0, s9
	v_lshl_add_u64 v[0:1], s[10:11], 0, v[40:41]
	v_readlane_b32 s10, v250, 51
	s_mov_b32 s9, m0
	s_mov_b32 m0, s10
	s_nop 0
	global_load_lds_dwordx4 v[0:1], off nt
	s_mov_b32 m0, s9
	s_add_u32 s9, s5, s34
	s_addc_u32 s12, s6, s48
	s_add_u32 s13, s7, s47
	s_addc_u32 s14, s8, 0
	s_and_b64 s[10:11], vcc, exec
	s_cselect_b32 s9, s9, s13
	s_cselect_b32 s10, s12, s14
	s_add_u32 s9, s9, s36
	s_addc_u32 s12, s10, 0
	s_and_b64 s[10:11], s[70:71], exec
	s_cselect_b32 s11, s1, s12
	s_cselect_b32 s10, s0, s9
	v_lshl_add_u64 v[0:1], s[10:11], 0, v[40:41]
	v_readlane_b32 s10, v250, 53
	s_mov_b32 s9, m0
	s_mov_b32 m0, s10
	s_nop 0
	global_load_lds_dwordx4 v[0:1], off nt
	s_mov_b32 m0, s9
	s_add_u32 s9, s5, s18
	v_readlane_b32 s10, v250, 0
	s_addc_u32 s12, s6, s10
	v_readlane_b32 s10, v249, 62
	s_add_u32 s13, s7, s10
	s_addc_u32 s14, s8, 0
	s_and_b64 s[10:11], s[62:63], exec
	s_cselect_b32 s9, s9, s13
	s_cselect_b32 s10, s12, s14
	s_add_u32 s9, s9, s19
	s_addc_u32 s12, s10, 0
	s_and_b64 s[10:11], s[70:71], exec
	s_cselect_b32 s11, s1, s12
	s_cselect_b32 s10, s0, s9
	v_lshl_add_u64 v[0:1], s[10:11], 0, v[40:41]
	v_readlane_b32 s10, v250, 55
	s_mov_b32 s9, m0
	s_mov_b32 m0, s10
	s_nop 0
	global_load_lds_dwordx4 v[0:1], off nt
	s_mov_b32 m0, s9
	s_add_u32 s9, s5, s16
	s_addc_u32 s12, s6, s26
	s_add_u32 s13, s7, s67
	s_addc_u32 s14, s8, 0
	s_and_b64 s[10:11], s[96:97], exec
	s_cselect_b32 s9, s9, s13
	s_cselect_b32 s10, s12, s14
	s_add_u32 s9, s9, s17
	s_addc_u32 s12, s10, 0
	s_and_b64 s[10:11], s[70:71], exec
	s_cselect_b32 s11, s1, s12
	s_cselect_b32 s10, s0, s9
	v_lshl_add_u64 v[0:1], s[10:11], 0, v[40:41]
	v_readlane_b32 s10, v250, 57
	s_mov_b32 s9, m0
	s_mov_b32 m0, s10
	s_nop 0
	global_load_lds_dwordx4 v[0:1], off nt
	s_mov_b32 m0, s9
	s_add_u32 s9, s5, s61
	s_addc_u32 s12, s6, s49
	s_add_u32 s13, s7, s52
	s_addc_u32 s14, s8, 0
	s_and_b64 s[10:11], s[84:85], exec
	s_cselect_b32 s9, s9, s13
	s_cselect_b32 s10, s12, s14
	s_add_u32 s9, s9, s53
	s_addc_u32 s12, s10, 0
	s_and_b64 s[10:11], s[70:71], exec
	s_cselect_b32 s11, s1, s12
	s_cselect_b32 s10, s0, s9
	v_lshl_add_u64 v[0:1], s[10:11], 0, v[40:41]
	v_readlane_b32 s10, v250, 59
	s_mov_b32 s9, m0
	s_mov_b32 m0, s10
	s_nop 0
	global_load_lds_dwordx4 v[0:1], off nt
	s_mov_b32 m0, s9
	s_mov_b32 s84, s33
	s_add_u32 s9, s5, s57
	s_addc_u32 s12, s6, s84
	s_add_u32 s13, s7, s91
	s_addc_u32 s14, s8, 0
	s_and_b64 s[10:11], s[30:31], exec
	s_cselect_b32 s9, s9, s13
	s_cselect_b32 s10, s12, s14
	s_add_u32 s9, s9, s58
	s_addc_u32 s12, s10, 0
	s_and_b64 s[10:11], s[70:71], exec
	s_cselect_b32 s11, s1, s12
	s_cselect_b32 s10, s0, s9
	v_lshl_add_u64 v[0:1], s[10:11], 0, v[40:41]
	v_readlane_b32 s10, v250, 61
	s_mov_b32 s9, m0
	s_mov_b32 m0, s10
	s_nop 0
	global_load_lds_dwordx4 v[0:1], off nt
	s_mov_b32 m0, s9
	s_add_u32 s9, s5, s59
	s_addc_u32 s12, s6, s83
	s_add_u32 s13, s7, s93
	s_addc_u32 s14, s8, 0
	s_and_b64 s[10:11], s[20:21], exec
	s_cselect_b32 s9, s9, s13
	s_cselect_b32 s10, s12, s14
	s_add_u32 s9, s9, s60
	s_addc_u32 s12, s10, 0
	s_and_b64 s[10:11], s[70:71], exec
	s_cselect_b32 s11, s1, s12
	s_cselect_b32 s10, s0, s9
	v_lshl_add_u64 v[0:1], s[10:11], 0, v[40:41]
	v_readlane_b32 s10, v250, 63
	s_mov_b32 s9, m0
	s_mov_b32 m0, s10
	s_nop 0
	global_load_lds_dwordx4 v[0:1], off nt
	s_mov_b32 m0, s9
	s_add_u32 s9, s5, s94
	s_addc_u32 s12, s6, s80
	s_add_u32 s13, s7, s82
	s_addc_u32 s14, s8, 0
	s_and_b64 s[10:11], s[72:73], exec
	s_cselect_b32 s9, s9, s13
	s_cselect_b32 s10, s12, s14
	s_add_u32 s9, s9, s56
	s_addc_u32 s12, s10, 0
	s_and_b64 s[10:11], s[86:87], exec
	s_cselect_b32 s11, s1, s12
	s_cselect_b32 s10, s0, s9
	v_lshl_add_u64 v[0:1], s[10:11], 0, v[40:41]
	v_readlane_b32 s10, v251, 1
	s_mov_b32 s9, m0
	s_mov_b32 m0, s10
	s_nop 0
	global_load_lds_dwordx4 v[0:1], off nt
	s_mov_b32 m0, s9
	s_add_u32 s9, s5, s77
	s_addc_u32 s12, s6, s78
	s_add_u32 s13, s7, s79
	s_addc_u32 s14, s8, 0
	s_and_b64 s[10:11], s[74:75], exec
	s_cselect_b32 s9, s9, s13
	s_cselect_b32 s10, s12, s14
	s_add_u32 s9, s9, s27
	s_addc_u32 s12, s10, 0
	s_and_b64 s[10:11], s[86:87], exec
	s_cselect_b32 s11, s1, s12
	s_cselect_b32 s10, s0, s9
	v_lshl_add_u64 v[0:1], s[10:11], 0, v[40:41]
	v_readlane_b32 s10, v251, 3
	s_mov_b32 s9, m0
	s_mov_b32 m0, s10
	s_nop 0
	global_load_lds_dwordx4 v[0:1], off nt
	s_mov_b32 m0, s9
	s_add_u32 s9, s5, s24
	s_addc_u32 s12, s6, s90
	s_add_u32 s13, s7, s81
	s_addc_u32 s14, s8, 0
	s_and_b64 s[10:11], s[88:89], exec
	s_cselect_b32 s9, s9, s13
	s_cselect_b32 s10, s12, s14
	s_add_u32 s9, s9, s66
	s_addc_u32 s12, s10, 0
	s_and_b64 s[10:11], s[86:87], exec
	s_cselect_b32 s11, s1, s12
	s_cselect_b32 s10, s0, s9
	v_lshl_add_u64 v[0:1], s[10:11], 0, v[40:41]
	v_readlane_b32 s10, v251, 5
	s_mov_b32 s9, m0
	s_mov_b32 m0, s10
	s_nop 0
	global_load_lds_dwordx4 v[0:1], off nt
	s_mov_b32 m0, s9
	s_add_u32 s5, s5, s22
	s_addc_u32 s9, s6, s64
	s_add_u32 s10, s7, s65
	s_addc_u32 s8, s8, 0
	s_and_b64 s[6:7], s[68:69], exec
	s_cselect_b32 s5, s5, s10
	s_cselect_b32 s6, s9, s8
	s_add_u32 s5, s5, s76
	s_addc_u32 s8, s6, 0
	s_and_b64 s[6:7], s[86:87], exec
	s_cselect_b32 s1, s1, s8
	s_cselect_b32 s0, s0, s5
	v_lshl_add_u64 v[0:1], s[0:1], 0, v[40:41]
	v_readlane_b32 s1, v251, 7
	s_mov_b32 s0, m0
	s_mov_b32 m0, s1
	s_nop 0
	global_load_lds_dwordx4 v[0:1], off nt
	s_mov_b32 m0, s0
	v_readlane_b32 s62, v255, 19
	s_mov_b32 s97, s26
	s_mov_b32 s26, s83
	v_readlane_b32 s30, v255, 21
	v_readlane_b32 s82, v255, 30
	v_readlane_b32 s72, v255, 24
	v_readlane_b32 s63, v255, 20
	s_mov_b32 s96, s67
	v_readlane_b32 s85, v254, 48
	v_readlane_b32 s67, v254, 47
	v_readlane_b32 s33, v255, 23
	v_readlane_b32 s31, v255, 22
	v_readlane_b32 s80, v255, 29
	v_readlane_b32 s83, v255, 31
	v_readlane_b32 s73, v255, 25
	v_readlane_b32 s78, v255, 27
	v_readlane_b32 s79, v255, 28
	s_mov_b32 s75, s40
	v_readlane_b32 s74, v255, 26
	v_readlane_b32 s90, v255, 32
	s_mov_b32 s81, s41
	s_mov_b64 s[88:89], s[50:51]
